# context-attention tasks: the workgroup stages its (batch, head) K rows and V^T rows into LDS once per round with coalesced loads; MFMA fragments read from LDS (confirmed with attention phases repeated
# speedup vs baseline: 1.0222x; 1.0062x over previous
.LBB0_522:
	v_mov_b64_e32 v[152:153], 0x240
	v_mov_b64_e32 v[154:155], 0x23f
	v_mov_b64_e32 v[156:157], 0x7e0
	v_mov_b64_e32 v[158:159], 0x7df
	v_mov_b64_e32 v[160:161], 0x6c0
	v_mov_b64_e32 v[162:163], 0x6bf
	s_lshl_b32 s0, s57, 3
	s_add_i32 s2, s0, s56
	v_readlane_b32 s70, v255, 11
	v_readlane_b32 s30, v255, 13
	v_readlane_b32 s34, v255, 15
	v_readlane_b32 s38, v255, 17
	s_cmpk_gt_i32 s2, 0xfff
	v_readlane_b32 s78, v255, 5
	v_readlane_b32 s72, v255, 6
	v_readlane_b32 s71, v255, 12
	v_readlane_b32 s31, v255, 14
	v_readlane_b32 s35, v255, 16
	v_readlane_b32 s39, v255, 18
	s_mov_b64 s[74:75], 0xc80000
	s_waitcnt vmcnt(0) lgkmcnt(0)
	s_barrier
	v_readlane_b32 s73, v255, 7
	s_cbranch_scc1 .LBB0_525
	v_mul_u32_u24_e32 v0, 0x9000, v118
	v_and_b32_e32 v1, 64, v188
	v_add_lshl_u32 v32, v0, v36, 1
	v_xor_b32_e32 v0, 16, v188
	v_add_u32_e32 v1, 64, v1
	v_cmp_lt_i32_e32 vcc, v0, v1
	v_xor_b32_e32 v2, 32, v188
	s_lshl_b32 s0, s57, 5
	v_cndmask_b32_e32 v0, v188, v0, vcc
	v_cmp_lt_i32_e32 vcc, v2, v1
	s_lshl_b32 s1, s56, 2
	s_add_i32 s4, s0, s1
	v_cndmask_b32_e32 v1, v188, v2, vcc
	s_lshl_b32 s0, s57, 7
	s_lshl_b32 s1, s56, 4
	s_lshl_b32 s3, s10, 3
	v_lshl_add_u32 v148, v47, 12, v51
	v_mov_b32_e32 v33, v149
	v_lshlrev_b32_e32 v78, 2, v0
	v_lshlrev_b32_e32 v79, 2, v1
	s_lshl_b32 s5, s10, 5
	s_add_i32 s11, s0, s1
	s_lshl_b32 s10, s10, 7
	s_mov_b32 s19, 0x40000
	s_mov_b32 s20, 0x120000
	v_mul_u32_u24_e32 v246, 0x90, v47
	v_add_u32_e32 v246, v246, v51
	v_mul_u32_u24_e32 v247, 0x210, v118
	v_add_u32_e32 v247, v247, v51
	v_and_b32_e32 v252, 7, v118
	v_lshlrev_b32_e32 v252, 4, v252
	v_lshlrev_b32_e32 v253, 4, v128
	v_and_b32_e32 v253, 0x1f0, v253
	v_mov_b32_e32 v248, v128
.LBB0_524:
	s_barrier
	s_lshr_b32 s16, s2, 8
	s_lshl_b32 s0, s16, 9
	s_lshl_b32 s16, s16, 20
	s_bfe_u32 s17, s2, 0x40004
	s_lshl_b32 s1, s17, 7
	s_add_i32 s16, s16, s1
	s_addk_i32 s16, 0x800
	s_mul_i32 s17, s17, 0x480000
	s_add_i32 s0, s0, s17
	s_add_u32 s16, s44, s16
	s_addc_u32 s17, s45, 0
	s_add_u32 s0, s46, s0
	s_addc_u32 s1, s47, 0
	v_mov_b32_e32 v224, v248
	v_ashrrev_i32_e32 v224, 3, v224
	v_lshl_add_u32 v222, v224, 12, v252
	global_load_dwordx4 v[190:193], v222, s[16:17]
	v_mul_u32_u24_e32 v224, 0x90, v224
	v_add_u32_e32 v224, v224, v252
	v_add_u32_e32 v225, 0x200, v248
	v_ashrrev_i32_e32 v225, 3, v225
	v_lshl_add_u32 v222, v225, 12, v252
	global_load_dwordx4 v[194:197], v222, s[16:17]
	v_mul_u32_u24_e32 v225, 0x90, v225
	v_add_u32_e32 v225, v225, v252
	v_add_u32_e32 v226, 0x400, v248
	v_ashrrev_i32_e32 v226, 3, v226
	v_lshl_add_u32 v222, v226, 12, v252
	global_load_dwordx4 v[198:201], v222, s[16:17]
	v_mul_u32_u24_e32 v226, 0x90, v226
	v_add_u32_e32 v226, v226, v252
	v_add_u32_e32 v227, 0x600, v248
	v_ashrrev_i32_e32 v227, 3, v227
	v_lshl_add_u32 v222, v227, 12, v252
	global_load_dwordx4 v[202:205], v222, s[16:17]
	v_mul_u32_u24_e32 v227, 0x90, v227
	v_add_u32_e32 v227, v227, v252
	v_mov_b32_e32 v228, v248
	v_ashrrev_i32_e32 v228, 5, v228
	v_mul_u32_u24_e32 v222, 0x12000, v228
	v_add_u32_e32 v222, v222, v253
	global_load_dwordx4 v[206:209], v222, s[0:1]
	v_mul_u32_u24_e32 v228, 0x210, v228
	v_add_u32_e32 v228, v228, v253
	v_add_u32_e32 v229, 0x200, v248
	v_ashrrev_i32_e32 v229, 5, v229
	v_mul_u32_u24_e32 v222, 0x12000, v229
	v_add_u32_e32 v222, v222, v253
	global_load_dwordx4 v[210:213], v222, s[0:1]
	v_mul_u32_u24_e32 v229, 0x210, v229
	v_add_u32_e32 v229, v229, v253
	v_add_u32_e32 v230, 0x400, v248
	v_ashrrev_i32_e32 v230, 5, v230
	v_mul_u32_u24_e32 v222, 0x12000, v230
	v_add_u32_e32 v222, v222, v253
	global_load_dwordx4 v[214:217], v222, s[0:1]
	v_mul_u32_u24_e32 v230, 0x210, v230
	v_add_u32_e32 v230, v230, v253
	v_add_u32_e32 v231, 0x600, v248
	v_ashrrev_i32_e32 v231, 5, v231
	v_mul_u32_u24_e32 v222, 0x12000, v231
	v_add_u32_e32 v222, v222, v253
	global_load_dwordx4 v[218:221], v222, s[0:1]
	v_mul_u32_u24_e32 v231, 0x210, v231
	v_add_u32_e32 v231, v231, v253
	s_waitcnt vmcnt(7)
	ds_write_b128 v224, v[190:193]
	s_waitcnt vmcnt(6)
	ds_write_b128 v225, v[194:197]
	s_waitcnt vmcnt(5)
	ds_write_b128 v226, v[198:201]
	s_waitcnt vmcnt(4)
	ds_write_b128 v227, v[202:205]
	s_waitcnt vmcnt(3)
	ds_write_b128 v228, v[206:209] offset:36864
	s_waitcnt vmcnt(2)
	ds_write_b128 v229, v[210:213] offset:36864
	s_waitcnt vmcnt(1)
	ds_write_b128 v230, v[214:217] offset:36864
	s_waitcnt vmcnt(0)
	ds_write_b128 v231, v[218:221] offset:36864
	s_waitcnt lgkmcnt(0)
	s_barrier
	s_and_b32 s0, s2, 0xffffff00
	s_and_b32 s1, s11, 0xf0
	v_or_b32_e32 v0, s1, v118
	s_and_b32 s18, s4, 0x3c0
	s_ashr_i32 s1, s0, 31
	s_lshl_b32 s6, s18, 1
	s_lshl_b64 s[16:17], s[0:1], 12
	s_add_u32 s16, s44, s16
	v_or_b32_e32 v34, s0, v0
	s_addc_u32 s17, s45, s17
	v_ashrrev_i32_e32 v35, 31, v34
	s_add_u32 s16, s16, s6
	v_lshlrev_b64 v[0:1], 12, v[34:35]
	s_addc_u32 s17, s17, 0
	v_lshl_add_u64 v[0:1], s[44:45], 0, v[0:1]
	v_lshl_add_u64 v[40:41], s[16:17], 0, v[148:149]
	s_movk_i32 s16, 0x4000
	v_lshl_add_u64 v[0:1], v[0:1], 0, s[6:7]
	v_add_co_u32_e32 v12, vcc, s16, v40
	v_lshl_add_u64 v[4:5], v[36:37], 1, v[0:1]
	s_nop 0
	v_addc_co_u32_e32 v13, vcc, 0, v41, vcc
	global_load_dwordx4 v[0:3], v[4:5], off
	s_nop 0
	global_load_dwordx4 v[4:7], v[4:5], off offset:64
	ds_read_b128 v[190:193], v246
	ds_read_b128 v[194:197], v246 offset:64
	ds_read_b128 v[198:201], v246 offset:576
	ds_read_b128 v[202:205], v246 offset:640
	ds_read_b128 v[206:209], v246 offset:4608
	ds_read_b128 v[210:213], v246 offset:4672
	ds_read_b128 v[214:217], v246 offset:5184
	ds_read_b128 v[218:221], v246 offset:5248
	ds_read_b128 v[222:225], v246 offset:9216
	ds_read_b128 v[226:229], v246 offset:9280
	ds_read_b128 v[230:233], v246 offset:9792
	ds_read_b128 v[234:237], v246 offset:9856
	ds_read_b128 v[238:241], v246 offset:13824
	ds_read_b128 v[242:245], v246 offset:13888
	s_nop 0
	s_nop 0
	s_nop 0
	s_mul_i32 s18, s18, 0x12000
	s_add_u32 s16, s46, s18
	s_addc_u32 s17, s47, 0
	s_waitcnt vmcnt(0)
	s_waitcnt lgkmcnt(13)
	v_mfma_f32_16x16x32_bf16 v[20:23], v[190:193], v[0:3], 0
	s_waitcnt lgkmcnt(12)
	v_mfma_f32_16x16x32_bf16 v[16:19], v[194:197], v[4:7], v[20:23]
	ds_read_b128 v[190:193], v246 offset:14400
	ds_read_b128 v[194:197], v246 offset:14464
	s_nop 7
	v_pk_mul_f32 v[74:75], v[18:19], s[12:13] op_sel_hi:[1,0]
	v_pk_mul_f32 v[76:77], v[16:17], s[12:13] op_sel_hi:[1,0]
	v_max_f32_e32 v16, v74, v75
	v_max3_f32 v24, v76, v77, v16
	s_nop 1
	s_nop 0
	s_waitcnt lgkmcnt(13)
	v_mfma_f32_16x16x32_bf16 v[8:11], v[198:201], v[0:3], 0
	s_waitcnt lgkmcnt(12)
	v_mfma_f32_16x16x32_bf16 v[8:11], v[202:205], v[4:7], v[8:11]
	ds_read_b128 v[198:201], v246 offset:18432
	ds_read_b128 v[202:205], v246 offset:18496
	s_nop 7
	v_pk_mul_f32 v[70:71], v[10:11], s[12:13] op_sel_hi:[1,0]
	v_pk_mul_f32 v[72:73], v[8:9], s[12:13] op_sel_hi:[1,0]
	v_max_f32_e32 v8, v70, v71
	v_max3_f32 v8, v72, v73, v8
	v_max3_f32 v24, v24, s69, v8
	s_nop 1
	s_nop 0
	s_waitcnt lgkmcnt(13)
	v_mfma_f32_16x16x32_bf16 v[16:19], v[206:209], v[0:3], 0
	s_waitcnt lgkmcnt(12)
	v_mfma_f32_16x16x32_bf16 v[16:19], v[210:213], v[4:7], v[16:19]
	ds_read_b128 v[206:209], v246 offset:19008
	ds_read_b128 v[210:213], v246 offset:19072
	s_nop 7
	v_pk_mul_f32 v[66:67], v[18:19], s[12:13] op_sel_hi:[1,0]
	v_pk_mul_f32 v[68:69], v[16:17], s[12:13] op_sel_hi:[1,0]
	v_max_f32_e32 v16, v66, v67
	v_max3_f32 v25, v68, v69, v16
	s_nop 1
	s_nop 0
	s_waitcnt lgkmcnt(13)
	v_mfma_f32_16x16x32_bf16 v[8:11], v[214:217], v[0:3], 0
	s_waitcnt lgkmcnt(12)
	v_mfma_f32_16x16x32_bf16 v[8:11], v[218:221], v[4:7], v[8:11]
	ds_read_b128 v[214:217], v246 offset:23040
	ds_read_b128 v[218:221], v246 offset:23104
	s_nop 7
	v_pk_mul_f32 v[62:63], v[10:11], s[12:13] op_sel_hi:[1,0]
	v_pk_mul_f32 v[64:65], v[8:9], s[12:13] op_sel_hi:[1,0]
	v_max_f32_e32 v8, v62, v63
	v_max3_f32 v8, v64, v65, v8
	v_max3_f32 v24, v24, v25, v8
	s_nop 1
	s_nop 0
	s_waitcnt lgkmcnt(13)
	v_mfma_f32_16x16x32_bf16 v[16:19], v[222:225], v[0:3], 0
	s_waitcnt lgkmcnt(12)
	v_mfma_f32_16x16x32_bf16 v[16:19], v[226:229], v[4:7], v[16:19]
	ds_read_b128 v[222:225], v246 offset:23616
	ds_read_b128 v[226:229], v246 offset:23680
	s_nop 7
	v_pk_mul_f32 v[58:59], v[18:19], s[12:13] op_sel_hi:[1,0]
	v_pk_mul_f32 v[60:61], v[16:17], s[12:13] op_sel_hi:[1,0]
	v_max_f32_e32 v16, v58, v59
	v_max3_f32 v25, v60, v61, v16
	s_nop 1
	s_nop 0
	s_waitcnt lgkmcnt(13)
	v_mfma_f32_16x16x32_bf16 v[8:11], v[230:233], v[0:3], 0
	s_waitcnt lgkmcnt(12)
	v_mfma_f32_16x16x32_bf16 v[8:11], v[234:237], v[4:7], v[8:11]
	ds_read_b128 v[230:233], v246 offset:27648
	ds_read_b128 v[234:237], v246 offset:27712
	s_nop 7
	v_pk_mul_f32 v[54:55], v[10:11], s[12:13] op_sel_hi:[1,0]
	v_pk_mul_f32 v[56:57], v[8:9], s[12:13] op_sel_hi:[1,0]
	v_max_f32_e32 v8, v54, v55
	v_max3_f32 v8, v56, v57, v8
	v_max3_f32 v24, v24, v25, v8
	s_nop 1
	s_nop 0
	s_waitcnt lgkmcnt(13)
	v_mfma_f32_16x16x32_bf16 v[16:19], v[238:241], v[0:3], 0
	s_waitcnt lgkmcnt(12)
	v_mfma_f32_16x16x32_bf16 v[16:19], v[242:245], v[4:7], v[16:19]
	ds_read_b128 v[238:241], v246 offset:28224
	ds_read_b128 v[242:245], v246 offset:28288
	s_nop 7
	v_pk_mul_f32 v[50:51], v[18:19], s[12:13] op_sel_hi:[1,0]
	v_pk_mul_f32 v[52:53], v[16:17], s[12:13] op_sel_hi:[1,0]
	v_max_f32_e32 v16, v50, v51
	v_max3_f32 v25, v52, v53, v16
	s_nop 1
	s_nop 0
	s_waitcnt lgkmcnt(13)
	v_mfma_f32_16x16x32_bf16 v[8:11], v[190:193], v[0:3], 0
	s_waitcnt lgkmcnt(12)
	v_mfma_f32_16x16x32_bf16 v[8:11], v[194:197], v[4:7], v[8:11]
	ds_read_b128 v[190:193], v246 offset:32256
	ds_read_b128 v[194:197], v246 offset:32320
	s_nop 7
	v_pk_mul_f32 v[46:47], v[10:11], s[12:13] op_sel_hi:[1,0]
	v_pk_mul_f32 v[48:49], v[8:9], s[12:13] op_sel_hi:[1,0]
	v_max_f32_e32 v8, v46, v47
	v_max3_f32 v8, v48, v49, v8
	v_max3_f32 v24, v24, v25, v8
	s_nop 1
	s_nop 0
	s_waitcnt lgkmcnt(13)
	v_mfma_f32_16x16x32_bf16 v[16:19], v[198:201], v[0:3], 0
	s_waitcnt lgkmcnt(12)
	v_mfma_f32_16x16x32_bf16 v[16:19], v[202:205], v[4:7], v[16:19]
	ds_read_b128 v[198:201], v246 offset:32832
	ds_read_b128 v[202:205], v246 offset:32896
	s_nop 7
	v_pk_mul_f32 v[42:43], v[18:19], s[12:13] op_sel_hi:[1,0]
	v_pk_mul_f32 v[44:45], v[16:17], s[12:13] op_sel_hi:[1,0]
	v_max_f32_e32 v16, v42, v43
	v_max3_f32 v25, v44, v45, v16
	s_nop 1
	s_nop 0
	s_waitcnt lgkmcnt(13)
	v_mfma_f32_16x16x32_bf16 v[8:11], v[206:209], v[0:3], 0
	s_waitcnt lgkmcnt(12)
	v_mfma_f32_16x16x32_bf16 v[8:11], v[210:213], v[4:7], v[8:11]
	s_nop 7
	v_pk_mul_f32 v[28:29], v[10:11], s[12:13] op_sel_hi:[1,0]
	v_pk_mul_f32 v[30:31], v[8:9], s[12:13] op_sel_hi:[1,0]
	v_max_f32_e32 v8, v28, v29
	v_max3_f32 v8, v30, v31, v8
	v_max3_f32 v84, v24, v25, v8
	s_nop 1
	s_nop 0
	s_waitcnt lgkmcnt(11)
	v_mfma_f32_16x16x32_bf16 v[16:19], v[214:217], v[0:3], 0
	s_waitcnt lgkmcnt(10)
	v_mfma_f32_16x16x32_bf16 v[16:19], v[218:221], v[4:7], v[16:19]
	s_nop 7
	v_pk_mul_f32 v[24:25], v[18:19], s[12:13] op_sel_hi:[1,0]
	v_pk_mul_f32 v[26:27], v[16:17], s[12:13] op_sel_hi:[1,0]
	v_max_f32_e32 v16, v24, v25
	v_max3_f32 v85, v26, v27, v16
	s_nop 1
	s_waitcnt lgkmcnt(9)
	v_mfma_f32_16x16x32_bf16 v[8:11], v[222:225], v[0:3], 0
	s_waitcnt lgkmcnt(8)
	v_mfma_f32_16x16x32_bf16 v[10:13], v[226:229], v[4:7], v[8:11]
	s_nop 7
	v_pk_mul_f32 v[8:9], v[12:13], s[12:13] op_sel_hi:[1,0]
	v_pk_mul_f32 v[22:23], v[10:11], s[12:13] op_sel_hi:[1,0]
	v_max_f32_e32 v10, v8, v9
	v_max3_f32 v10, v22, v23, v10
	v_max3_f32 v92, v84, v85, v10
	s_nop 1
	s_waitcnt lgkmcnt(7)
	v_mfma_f32_16x16x32_bf16 v[16:19], v[230:233], v[0:3], 0
	s_waitcnt lgkmcnt(6)
	v_mfma_f32_16x16x32_bf16 v[16:19], v[234:237], v[4:7], v[16:19]
	s_nop 7
	v_pk_mul_f32 v[10:11], v[18:19], s[12:13] op_sel_hi:[1,0]
	v_pk_mul_f32 v[16:17], v[16:17], s[12:13] op_sel_hi:[1,0]
	v_max_f32_e32 v18, v10, v11
	v_max3_f32 v93, v16, v17, v18
	s_nop 1
	s_waitcnt lgkmcnt(5)
	v_mfma_f32_16x16x32_bf16 v[12:15], v[238:241], v[0:3], 0
	s_waitcnt lgkmcnt(4)
	v_mfma_f32_16x16x32_bf16 v[18:21], v[242:245], v[4:7], v[12:15]
	s_nop 7
	v_pk_mul_f32 v[12:13], v[20:21], s[12:13] op_sel_hi:[1,0]
	v_pk_mul_f32 v[18:19], v[18:19], s[12:13] op_sel_hi:[1,0]
	v_max_f32_e32 v14, v12, v13
	v_max3_f32 v14, v18, v19, v14
	v_max3_f32 v96, v92, v93, v14
	s_nop 1
	s_waitcnt lgkmcnt(3)
	v_mfma_f32_16x16x32_bf16 v[80:83], v[190:193], v[0:3], 0
	s_waitcnt lgkmcnt(2)
	v_mfma_f32_16x16x32_bf16 v[80:83], v[194:197], v[4:7], v[80:83]
	s_nop 7
	v_pk_mul_f32 v[14:15], v[82:83], s[12:13] op_sel_hi:[1,0]
	v_pk_mul_f32 v[20:21], v[80:81], s[12:13] op_sel_hi:[1,0]
	v_max_f32_e32 v40, v14, v15
	v_max3_f32 v40, v20, v21, v40
	s_waitcnt lgkmcnt(1)
	v_mfma_f32_16x16x32_bf16 v[0:3], v[198:201], v[0:3], 0
	s_waitcnt lgkmcnt(0)
	v_mfma_f32_16x16x32_bf16 v[2:5], v[202:205], v[4:7], v[0:3]
	s_nop 7
	v_pk_mul_f32 v[0:1], v[4:5], s[12:13] op_sel_hi:[1,0]
	v_pk_mul_f32 v[2:3], v[2:3], s[12:13] op_sel_hi:[1,0]
	v_max_f32_e32 v4, v0, v1
	v_max3_f32 v4, v2, v3, v4
	v_max3_f32 v4, v96, v40, v4
	ds_bpermute_b32 v5, v78, v4
	s_lshl_b64 s[0:1], s[0:1], 1
	s_add_u32 s0, s16, s0
	s_addc_u32 s1, s17, s1
	v_lshl_add_u64 v[40:41], s[0:1], 0, v[32:33]
	ds_read_b128 v[190:193], v247 offset:36864
	ds_read_b128 v[194:197], v247 offset:45312
	ds_read_b128 v[198:201], v247 offset:53760
	ds_read_b128 v[202:205], v247 offset:62208
	ds_read_b128 v[206:209], v247 offset:36928
	ds_read_b128 v[210:213], v247 offset:45376
	ds_read_b128 v[214:217], v247 offset:53824
	ds_read_b128 v[218:221], v247 offset:62272
	ds_read_b128 v[222:225], v247 offset:36992
	ds_read_b128 v[226:229], v247 offset:45440
	ds_read_b128 v[230:233], v247 offset:53888
	ds_read_b128 v[234:237], v247 offset:62336
	s_waitcnt lgkmcnt(0)
	v_max_f32_e32 v5, v5, v5
	v_max_f32_e32 v4, v4, v5
	ds_bpermute_b32 v5, v79, v4
	s_mov_b32 s0, 0x240000
	s_waitcnt lgkmcnt(0)
	v_max_f32_e32 v5, v5, v5
	v_max_f32_e32 v4, v4, v5
	v_sub_f32_e32 v6, v77, v4
	v_mul_f32_e32 v6, 0x3fb8aa3b, v6
	v_exp_f32_e32 v77, v6
	v_sub_f32_e32 v6, v74, v4
	v_mul_f32_e32 v6, 0x3fb8aa3b, v6
	v_exp_f32_e32 v74, v6
	v_sub_f32_e32 v6, v75, v4
	v_mul_f32_e32 v6, 0x3fb8aa3b, v6
	v_exp_f32_e32 v75, v6
	v_sub_f32_e32 v6, v72, v4
	v_mul_f32_e32 v6, 0x3fb8aa3b, v6
	v_exp_f32_e32 v72, v6
	v_sub_f32_e32 v6, v73, v4
	v_mul_f32_e32 v6, 0x3fb8aa3b, v6
	v_exp_f32_e32 v73, v6
	v_sub_f32_e32 v6, v70, v4
	v_mul_f32_e32 v6, 0x3fb8aa3b, v6
	v_exp_f32_e32 v70, v6
	v_sub_f32_e32 v6, v71, v4
	v_mul_f32_e32 v6, 0x3fb8aa3b, v6
	v_exp_f32_e32 v71, v6
	v_sub_f32_e32 v6, v68, v4
	v_mul_f32_e32 v6, 0x3fb8aa3b, v6
	v_exp_f32_e32 v68, v6
	v_sub_f32_e32 v6, v69, v4
	v_mul_f32_e32 v6, 0x3fb8aa3b, v6
	v_exp_f32_e32 v69, v6
	v_sub_f32_e32 v6, v66, v4
	v_mul_f32_e32 v6, 0x3fb8aa3b, v6
	v_exp_f32_e32 v66, v6
	v_sub_f32_e32 v6, v67, v4
	v_mul_f32_e32 v6, 0x3fb8aa3b, v6
	v_exp_f32_e32 v67, v6
	v_sub_f32_e32 v6, v64, v4
	v_mul_f32_e32 v6, 0x3fb8aa3b, v6
	v_exp_f32_e32 v64, v6
	v_sub_f32_e32 v6, v65, v4
	v_mul_f32_e32 v6, 0x3fb8aa3b, v6
	v_exp_f32_e32 v65, v6
	v_sub_f32_e32 v6, v62, v4
	v_mul_f32_e32 v6, 0x3fb8aa3b, v6
	v_exp_f32_e32 v62, v6
	v_sub_f32_e32 v6, v63, v4
	v_mul_f32_e32 v6, 0x3fb8aa3b, v6
	v_exp_f32_e32 v63, v6
	v_sub_f32_e32 v6, v60, v4
	v_mul_f32_e32 v6, 0x3fb8aa3b, v6
	v_exp_f32_e32 v60, v6
	v_sub_f32_e32 v6, v61, v4
	v_mul_f32_e32 v6, 0x3fb8aa3b, v6
	v_exp_f32_e32 v61, v6
	v_sub_f32_e32 v6, v58, v4
	v_mul_f32_e32 v6, 0x3fb8aa3b, v6
	v_exp_f32_e32 v58, v6
	v_sub_f32_e32 v6, v59, v4
	v_mul_f32_e32 v6, 0x3fb8aa3b, v6
	v_exp_f32_e32 v59, v6
	v_sub_f32_e32 v6, v56, v4
	v_mul_f32_e32 v6, 0x3fb8aa3b, v6
	v_exp_f32_e32 v56, v6
	v_sub_f32_e32 v6, v57, v4
	v_mul_f32_e32 v6, 0x3fb8aa3b, v6
	v_exp_f32_e32 v57, v6
	v_sub_f32_e32 v6, v54, v4
	v_mul_f32_e32 v6, 0x3fb8aa3b, v6
	v_exp_f32_e32 v54, v6
	v_sub_f32_e32 v6, v55, v4
	v_mul_f32_e32 v6, 0x3fb8aa3b, v6
	v_exp_f32_e32 v55, v6
	v_sub_f32_e32 v6, v52, v4
	v_mul_f32_e32 v6, 0x3fb8aa3b, v6
	v_exp_f32_e32 v52, v6
	v_sub_f32_e32 v6, v53, v4
	v_mul_f32_e32 v6, 0x3fb8aa3b, v6
	v_exp_f32_e32 v53, v6
	v_sub_f32_e32 v6, v50, v4
	v_mul_f32_e32 v6, 0x3fb8aa3b, v6
	v_exp_f32_e32 v50, v6
	v_sub_f32_e32 v6, v51, v4
	v_mul_f32_e32 v6, 0x3fb8aa3b, v6
	v_exp_f32_e32 v51, v6
	v_sub_f32_e32 v6, v48, v4
	v_mul_f32_e32 v6, 0x3fb8aa3b, v6
	v_exp_f32_e32 v48, v6
	v_sub_f32_e32 v6, v49, v4
	v_sub_f32_e32 v5, v76, v4
	v_mul_f32_e32 v6, 0x3fb8aa3b, v6
	v_mul_f32_e32 v5, 0x3fb8aa3b, v5
	v_exp_f32_e32 v49, v6
	v_sub_f32_e32 v6, v46, v4
	v_exp_f32_e32 v76, v5
	v_mul_f32_e32 v6, 0x3fb8aa3b, v6
	v_exp_f32_e32 v80, v6
	v_sub_f32_e32 v6, v47, v4
	v_mul_f32_e32 v6, 0x3fb8aa3b, v6
	v_exp_f32_e32 v81, v6
	v_sub_f32_e32 v6, v44, v4
	v_add_f32_e32 v5, 0, v76
	v_mul_f32_e32 v6, 0x3fb8aa3b, v6
	v_add_f32_e32 v5, v77, v5
	v_exp_f32_e32 v82, v6
	v_sub_f32_e32 v6, v45, v4
	v_add_f32_e32 v5, v74, v5
	v_mul_f32_e32 v6, 0x3fb8aa3b, v6
	v_add_f32_e32 v5, v75, v5
	v_exp_f32_e32 v83, v6
	v_sub_f32_e32 v6, v42, v4
	v_add_f32_e32 v5, v72, v5
	v_mul_f32_e32 v6, 0x3fb8aa3b, v6
	v_add_f32_e32 v5, v73, v5
	v_exp_f32_e32 v84, v6
	v_sub_f32_e32 v6, v43, v4
	v_add_f32_e32 v5, v70, v5
	v_mul_f32_e32 v6, 0x3fb8aa3b, v6
	v_add_f32_e32 v5, v71, v5
	v_exp_f32_e32 v85, v6
	v_sub_f32_e32 v6, v30, v4
	v_add_f32_e32 v5, v68, v5
	v_mul_f32_e32 v6, 0x3fb8aa3b, v6
	v_add_f32_e32 v5, v69, v5
	v_exp_f32_e32 v86, v6
	v_sub_f32_e32 v6, v31, v4
	v_add_f32_e32 v5, v66, v5
	v_mul_f32_e32 v6, 0x3fb8aa3b, v6
	v_add_f32_e32 v5, v67, v5
	v_exp_f32_e32 v87, v6
	v_sub_f32_e32 v6, v28, v4
	v_add_f32_e32 v5, v64, v5
	v_mul_f32_e32 v6, 0x3fb8aa3b, v6
	v_add_f32_e32 v5, v65, v5
	v_exp_f32_e32 v88, v6
	v_sub_f32_e32 v6, v29, v4
	v_add_f32_e32 v5, v62, v5
	v_mul_f32_e32 v6, 0x3fb8aa3b, v6
	v_add_f32_e32 v5, v63, v5
	v_exp_f32_e32 v89, v6
	v_sub_f32_e32 v6, v26, v4
	v_add_f32_e32 v5, v60, v5
	v_mul_f32_e32 v6, 0x3fb8aa3b, v6
	v_add_f32_e32 v5, v61, v5
	v_exp_f32_e32 v90, v6
	v_sub_f32_e32 v6, v27, v4
	v_add_f32_e32 v5, v58, v5
	v_mul_f32_e32 v6, 0x3fb8aa3b, v6
	v_add_f32_e32 v5, v59, v5
	v_exp_f32_e32 v91, v6
	v_sub_f32_e32 v6, v24, v4
	v_add_f32_e32 v5, v56, v5
	v_mul_f32_e32 v6, 0x3fb8aa3b, v6
	v_add_f32_e32 v5, v57, v5
	v_exp_f32_e32 v92, v6
	v_sub_f32_e32 v6, v25, v4
	v_add_f32_e32 v5, v54, v5
	v_mul_f32_e32 v6, 0x3fb8aa3b, v6
	v_add_f32_e32 v5, v55, v5
	v_exp_f32_e32 v93, v6
	v_sub_f32_e32 v6, v22, v4
	v_add_f32_e32 v5, v52, v5
	v_mul_f32_e32 v6, 0x3fb8aa3b, v6
	v_add_f32_e32 v5, v53, v5
	v_exp_f32_e32 v94, v6
	v_sub_f32_e32 v6, v23, v4
	v_add_f32_e32 v5, v50, v5
	v_mul_f32_e32 v6, 0x3fb8aa3b, v6
	v_add_f32_e32 v5, v51, v5
	v_exp_f32_e32 v95, v6
	v_sub_f32_e32 v6, v8, v4
	v_add_f32_e32 v5, v48, v5
	v_mul_f32_e32 v6, 0x3fb8aa3b, v6
	v_add_f32_e32 v5, v49, v5
	v_exp_f32_e32 v97, v6
	v_sub_f32_e32 v6, v9, v4
	v_add_f32_e32 v5, v80, v5
	v_mul_f32_e32 v6, 0x3fb8aa3b, v6
	v_add_f32_e32 v5, v81, v5
	v_exp_f32_e32 v100, v6
	v_sub_f32_e32 v6, v16, v4
	v_add_f32_e32 v5, v82, v5
	v_mul_f32_e32 v6, 0x3fb8aa3b, v6
	v_add_f32_e32 v5, v83, v5
	v_exp_f32_e32 v96, v6
	v_sub_f32_e32 v6, v17, v4
	v_add_f32_e32 v5, v84, v5
	v_mul_f32_e32 v6, 0x3fb8aa3b, v6
	v_add_f32_e32 v5, v85, v5
	v_exp_f32_e32 v98, v6
	v_sub_f32_e32 v6, v10, v4
	v_add_f32_e32 v5, v86, v5
	v_mul_f32_e32 v6, 0x3fb8aa3b, v6
	v_add_f32_e32 v5, v87, v5
	v_exp_f32_e32 v99, v6
	v_sub_f32_e32 v6, v11, v4
	v_add_f32_e32 v5, v88, v5
	v_mul_f32_e32 v6, 0x3fb8aa3b, v6
	v_add_f32_e32 v5, v89, v5
	v_exp_f32_e32 v101, v6
	v_sub_f32_e32 v6, v18, v4
	v_add_f32_e32 v5, v90, v5
	v_mul_f32_e32 v6, 0x3fb8aa3b, v6
	v_add_f32_e32 v5, v91, v5
	v_exp_f32_e32 v102, v6
	v_sub_f32_e32 v6, v19, v4
	v_add_f32_e32 v5, v92, v5
	v_mul_f32_e32 v6, 0x3fb8aa3b, v6
	v_add_f32_e32 v5, v93, v5
	v_exp_f32_e32 v104, v6
	v_sub_f32_e32 v6, v12, v4
	v_add_f32_e32 v5, v94, v5
	v_mul_f32_e32 v6, 0x3fb8aa3b, v6
	v_add_f32_e32 v5, v95, v5
	v_exp_f32_e32 v105, v6
	v_sub_f32_e32 v6, v13, v4
	v_add_f32_e32 v5, v97, v5
	v_mul_f32_e32 v6, 0x3fb8aa3b, v6
	v_add_f32_e32 v5, v100, v5
	v_exp_f32_e32 v108, v6
	v_sub_f32_e32 v6, v20, v4
	v_add_f32_e32 v5, v96, v5
	v_mul_f32_e32 v6, 0x3fb8aa3b, v6
	v_add_f32_e32 v5, v98, v5
	v_exp_f32_e32 v103, v6
	v_sub_f32_e32 v6, v21, v4
	v_add_f32_e32 v5, v99, v5
	v_mul_f32_e32 v6, 0x3fb8aa3b, v6
	v_add_f32_e32 v5, v101, v5
	v_exp_f32_e32 v106, v6
	v_sub_f32_e32 v6, v14, v4
	v_add_f32_e32 v5, v102, v5
	v_mul_f32_e32 v6, 0x3fb8aa3b, v6
	v_add_f32_e32 v5, v104, v5
	v_exp_f32_e32 v107, v6
	v_sub_f32_e32 v6, v15, v4
	v_add_f32_e32 v5, v105, v5
	v_mul_f32_e32 v6, 0x3fb8aa3b, v6
	v_sub_f32_e32 v2, v2, v4
	v_add_f32_e32 v5, v108, v5
	v_exp_f32_e32 v109, v6
	v_mul_f32_e32 v2, 0x3fb8aa3b, v2
	v_sub_f32_e32 v3, v3, v4
	v_add_f32_e32 v5, v103, v5
	v_exp_f32_e32 v110, v2
	v_mul_f32_e32 v3, 0x3fb8aa3b, v3
	v_sub_f32_e32 v0, v0, v4
	v_add_f32_e32 v5, v106, v5
	v_exp_f32_e32 v111, v3
	v_mul_f32_e32 v0, 0x3fb8aa3b, v0
	v_sub_f32_e32 v1, v1, v4
	v_add_f32_e32 v5, v107, v5
	v_exp_f32_e32 v112, v0
	v_mul_f32_e32 v1, 0x3fb8aa3b, v1
	v_add_f32_e32 v5, v109, v5
	v_exp_f32_e32 v113, v1
	v_add_f32_e32 v2, v110, v5
	v_add_f32_e32 v2, v111, v2
	v_add_f32_e32 v0, v112, v2
	v_add_f32_e32 v0, v113, v0
	ds_bpermute_b32 v1, v78, v0
	s_nop 0
	s_mov_b32 s0, 0x360000
	s_nop 0
	s_waitcnt lgkmcnt(0)
	v_add_f32_e32 v114, v0, v1
	ds_bpermute_b32 v115, v79, v114
	v_cvt_pk_bf16_f32 v120, v76, v77
	v_cvt_pk_bf16_f32 v121, v74, v75
	v_cvt_pk_bf16_f32 v122, v72, v73
	v_cvt_pk_bf16_f32 v123, v70, v71
	s_waitcnt lgkmcnt(11)
	v_mfma_f32_16x16x32_bf16 v[0:3], v[190:193], v[120:123], 0
	s_waitcnt lgkmcnt(10)
	v_mfma_f32_16x16x32_bf16 v[4:7], v[194:197], v[120:123], 0
	s_waitcnt lgkmcnt(9)
	v_mfma_f32_16x16x32_bf16 v[8:11], v[198:201], v[120:123], 0
	s_waitcnt lgkmcnt(8)
	v_mfma_f32_16x16x32_bf16 v[20:23], v[202:205], v[120:123], 0
	ds_read_b128 v[190:193], v247 offset:37056
	ds_read_b128 v[194:197], v247 offset:45504
	ds_read_b128 v[198:201], v247 offset:53952
	ds_read_b128 v[202:205], v247 offset:62400
	v_cvt_pk_bf16_f32 v128, v68, v69
	v_cvt_pk_bf16_f32 v129, v66, v67
	v_cvt_pk_bf16_f32 v130, v64, v65
	v_cvt_pk_bf16_f32 v131, v62, v63
	s_waitcnt lgkmcnt(11)
	v_mfma_f32_16x16x32_bf16 v[0:3], v[206:209], v[128:131], v[0:3]
	s_waitcnt lgkmcnt(10)
	v_mfma_f32_16x16x32_bf16 v[4:7], v[210:213], v[128:131], v[4:7]
	s_waitcnt lgkmcnt(9)
	v_mfma_f32_16x16x32_bf16 v[8:11], v[214:217], v[128:131], v[8:11]
	s_waitcnt lgkmcnt(8)
	v_mfma_f32_16x16x32_bf16 v[12:15], v[218:221], v[128:131], v[20:23]
	ds_read_b128 v[206:209], v247 offset:37120
	ds_read_b128 v[210:213], v247 offset:45568
	ds_read_b128 v[214:217], v247 offset:54016
	ds_read_b128 v[218:221], v247 offset:62464
	s_nop 1
	v_cvt_pk_bf16_f32 v60, v60, v61
	v_cvt_pk_bf16_f32 v61, v58, v59
	v_cvt_pk_bf16_f32 v62, v56, v57
	v_cvt_pk_bf16_f32 v63, v54, v55
	s_waitcnt lgkmcnt(11)
	v_mfma_f32_16x16x32_bf16 v[0:3], v[222:225], v[60:63], v[0:3]
	s_waitcnt lgkmcnt(10)
	v_mfma_f32_16x16x32_bf16 v[4:7], v[226:229], v[60:63], v[4:7]
	s_waitcnt lgkmcnt(9)
	v_mfma_f32_16x16x32_bf16 v[8:11], v[230:233], v[60:63], v[8:11]
	s_waitcnt lgkmcnt(8)
	v_mfma_f32_16x16x32_bf16 v[12:15], v[234:237], v[60:63], v[12:15]
	ds_read_b128 v[222:225], v247 offset:37184
	ds_read_b128 v[226:229], v247 offset:45632
	ds_read_b128 v[230:233], v247 offset:54080
	ds_read_b128 v[234:237], v247 offset:62528
	v_cvt_pk_bf16_f32 v70, v52, v53
	v_cvt_pk_bf16_f32 v71, v50, v51
	v_cvt_pk_bf16_f32 v72, v48, v49
	v_cvt_pk_bf16_f32 v73, v80, v81
	s_waitcnt lgkmcnt(11)
	v_mfma_f32_16x16x32_bf16 v[0:3], v[190:193], v[70:73], v[0:3]
	s_waitcnt lgkmcnt(10)
	v_mfma_f32_16x16x32_bf16 v[4:7], v[194:197], v[70:73], v[4:7]
	s_waitcnt lgkmcnt(9)
	v_mfma_f32_16x16x32_bf16 v[8:11], v[198:201], v[70:73], v[8:11]
	s_waitcnt lgkmcnt(8)
	v_mfma_f32_16x16x32_bf16 v[12:15], v[202:205], v[70:73], v[12:15]
	ds_read_b128 v[190:193], v247 offset:37248
	ds_read_b128 v[194:197], v247 offset:45696
	ds_read_b128 v[198:201], v247 offset:54144
	ds_read_b128 v[202:205], v247 offset:62592
	v_cvt_pk_bf16_f32 v48, v82, v83
	v_cvt_pk_bf16_f32 v49, v84, v85
	v_cvt_pk_bf16_f32 v50, v86, v87
	v_cvt_pk_bf16_f32 v51, v88, v89
	s_waitcnt lgkmcnt(11)
	v_mfma_f32_16x16x32_bf16 v[0:3], v[206:209], v[48:51], v[0:3]
	s_waitcnt lgkmcnt(10)
	v_mfma_f32_16x16x32_bf16 v[4:7], v[210:213], v[48:51], v[4:7]
	s_waitcnt lgkmcnt(9)
	v_mfma_f32_16x16x32_bf16 v[8:11], v[214:217], v[48:51], v[8:11]
	s_waitcnt lgkmcnt(8)
	v_mfma_f32_16x16x32_bf16 v[12:15], v[218:221], v[48:51], v[12:15]
	ds_read_b128 v[206:209], v247 offset:37312
	ds_read_b128 v[210:213], v247 offset:45760
	ds_read_b128 v[214:217], v247 offset:54208
	ds_read_b128 v[218:221], v247 offset:62656
	v_cvt_pk_bf16_f32 v64, v90, v91
	v_cvt_pk_bf16_f32 v65, v92, v93
	v_cvt_pk_bf16_f32 v66, v94, v95
	v_cvt_pk_bf16_f32 v67, v97, v100
	s_waitcnt lgkmcnt(11)
	v_mfma_f32_16x16x32_bf16 v[0:3], v[222:225], v[64:67], v[0:3]
	s_waitcnt lgkmcnt(10)
	v_mfma_f32_16x16x32_bf16 v[4:7], v[226:229], v[64:67], v[4:7]
	s_waitcnt lgkmcnt(9)
	v_mfma_f32_16x16x32_bf16 v[8:11], v[230:233], v[64:67], v[8:11]
	s_waitcnt lgkmcnt(8)
	v_mfma_f32_16x16x32_bf16 v[12:15], v[234:237], v[64:67], v[12:15]
	v_cvt_pk_bf16_f32 v40, v96, v98
	v_cvt_pk_bf16_f32 v41, v99, v101
	v_cvt_pk_bf16_f32 v42, v102, v104
	v_cvt_pk_bf16_f32 v43, v105, v108
	s_waitcnt lgkmcnt(7)
	v_mfma_f32_16x16x32_bf16 v[0:3], v[190:193], v[40:43], v[0:3]
	s_waitcnt lgkmcnt(6)
	v_mfma_f32_16x16x32_bf16 v[4:7], v[194:197], v[40:43], v[4:7]
	s_waitcnt lgkmcnt(5)
	v_mfma_f32_16x16x32_bf16 v[8:11], v[198:201], v[40:43], v[8:11]
	s_waitcnt lgkmcnt(4)
	v_mfma_f32_16x16x32_bf16 v[12:15], v[202:205], v[40:43], v[12:15]
	s_waitcnt lgkmcnt(0)
	v_add_f32_e32 v44, v114, v115
	v_cvt_pk_bf16_f32 v40, v103, v106
	v_cvt_pk_bf16_f32 v41, v107, v109
	v_cvt_pk_bf16_f32 v42, v110, v111
	v_cvt_pk_bf16_f32 v43, v112, v113
	s_waitcnt lgkmcnt(3)
	v_mfma_f32_16x16x32_bf16 v[0:3], v[206:209], v[40:43], v[0:3]
	s_waitcnt lgkmcnt(2)
	v_mfma_f32_16x16x32_bf16 v[4:7], v[210:213], v[40:43], v[4:7]
	s_waitcnt lgkmcnt(1)
	v_mfma_f32_16x16x32_bf16 v[8:11], v[214:217], v[40:43], v[8:11]
	s_waitcnt lgkmcnt(0)
	v_mfma_f32_16x16x32_bf16 v[12:15], v[218:221], v[40:43], v[12:15]
	v_add_f32_e32 v16, 0, v44
	v_div_scale_f32 v17, s[0:1], v16, v16, 1.0
	v_rcp_f32_e32 v18, v17
	v_div_scale_f32 v19, vcc, 1.0, v16, 1.0
	s_add_i32 s2, s2, s3
	v_fma_f32 v20, -v17, v18, 1.0
	v_fmac_f32_e32 v18, v20, v18
	v_mul_f32_e32 v20, v19, v18
	v_fma_f32 v21, -v17, v20, v19
	v_fmac_f32_e32 v20, v21, v18
	v_fma_f32 v17, -v17, v20, v19
	v_div_fmas_f32 v17, v17, v18, v20
	v_lshlrev_b64 v[18:19], 11, v[34:35]
	v_div_fixup_f32 v16, v17, v16, 1.0
	v_lshl_add_u64 v[18:19], s[42:43], 0, v[18:19]
	v_lshl_add_u64 v[18:19], v[18:19], 0, s[6:7]
	v_pk_mul_f32 v[2:3], v[16:17], v[2:3] op_sel_hi:[0,1]
	v_pk_mul_f32 v[0:1], v[16:17], v[0:1] op_sel_hi:[0,1]
	v_lshl_add_u64 v[18:19], v[38:39], 1, v[18:19]
	v_cvt_pk_bf16_f32 v0, v0, v1
	v_cvt_pk_bf16_f32 v1, v2, v3
	v_pk_mul_f32 v[2:3], v[16:17], v[4:5] op_sel_hi:[0,1]
	global_store_dwordx2 v[18:19], v[0:1], off
	v_pk_mul_f32 v[0:1], v[16:17], v[6:7] op_sel_hi:[0,1]
	v_cvt_pk_bf16_f32 v2, v2, v3
	v_cvt_pk_bf16_f32 v3, v0, v1
	global_store_dwordx2 v[18:19], v[2:3], off offset:32
	v_pk_mul_f32 v[2:3], v[16:17], v[8:9] op_sel_hi:[0,1]
	v_pk_mul_f32 v[0:1], v[16:17], v[10:11] op_sel_hi:[0,1]
	v_cvt_pk_bf16_f32 v2, v2, v3
	v_cvt_pk_bf16_f32 v3, v0, v1
	s_add_i32 s4, s4, s5
	s_add_i32 s11, s11, s10
	global_store_dwordx2 v[18:19], v[2:3], off offset:64
	v_pk_mul_f32 v[2:3], v[16:17], v[12:13] op_sel_hi:[0,1]
	s_cmpk_gt_i32 s2, 0xfff
	v_pk_mul_f32 v[0:1], v[16:17], v[14:15] op_sel_hi:[0,1]
	v_cvt_pk_bf16_f32 v2, v2, v3
	v_cvt_pk_bf16_f32 v3, v0, v1
	global_store_dwordx2 v[18:19], v[2:3], off offset:96
	s_cbranch_scc0 .LBB0_524
